# up-projection GEMM visits its column tiles in descending order so the down GEMM reads the most recently written hidden columns first (cache residency); on top of the norm-phase loop rewrite
# speedup vs baseline: 1.0094x; 1.0086x over previous
; #define PG8_WAIT_V(n) asm volatile("s_waitcnt vmcnt(" #n ")" ::: "memory")
;     __host__ __device__ bool next(int i, Unit& u) const {
;     ...
;         int wgid = (int)L; { const int q = nwg / NXCD, r = nwg % NXCD, xcd = wgid % NXCD, off = wgid / NXCD; wgid = (xcd < r ? xcd * (q + 1) : r * (q + 1) + (xcd - r) * q) + off; }
;         const int nig = WGM * nN, gid = wgid / nig, fm = gid * WGM, gsz = (nM - fm) < WGM ? (nM - fm) : WGM;
; template <class Epi, class Sched, bool ALIGN_EPI = false, bool SP2 = false>
; __device__ __forceinline__ void gemm_phase(PG8_LAS unsigned char* lds, const Gemm g, const Sched& S, const Epi& E) {
;     const int tid = tidx(), wid = __builtin_amdgcn_readfirstlane(tid >> 6), lane = tid & 63, wr = wid >> 2, wc = wid & 3, fr = lane & 15, fq = lane >> 4;
;     const int K = g.K, nt = K / BK;
;     unsigned voffA[2], voffB[2];
; #pragma unroll
;     for (int i = 0; i < 2; ++i) { int R, C; stage_rc(tid * 16 + i * 8192, R, C); const int Rb = Epi::PERM ? ((R & ~31) + perm32(R & 31)) : R;
;         voffA[i] = (unsigned)(R * K + C) * 2u; voffB[i] = (unsigned)(Rb * K + C) * 2u; }
;     const size_t kstep = (size_t)(BK * 2);
;     const size_t hstep = (size_t)HALF * K * 2;
;     const size_t tstep = 2 * hstep;
;     const unsigned ldsw = (unsigned)wid * 1024u;
;     const int aoff = lds_byte(wr * 64 + fr, fq * 8), boff = lds_byte(wc * 32 + fr, fq * 8);
;     ...
;     Unit cur, nxt; int ui = 0;
;     if (!S.next(0, cur)) return;
;     f32x4 acc[2][2][4][2];
; #pragma unroll
;     for (int a = 0; a < 2; ++a)
; #pragma unroll
;         for (int b = 0; b < 2; ++b)
; #pragma unroll
;             for (int m = 0; m < 4; ++m)
; #pragma unroll
;                 for (int n = 0; n < 2; ++n) acc[a][b][m][n] = (f32x4){0.f, 0.f, 0.f, 0.f};
;     bf16x8 At[4][2], B0[2][2], B1[2][2];
;     const char* cA = (const char*)g.A + (size_t)cur.pm * tstep; const char* cB = (const char*)g.Bt + (size_t)cur.pn * tstep;
;     S.a_ready(cur);
;     if constexpr (SP2) {
;         PG8_STAGE(PG8_SB(0, 0), cB, voffB); PG8_STAGE(PG8_SB(0, 1), cB + hstep, voffB); PG8_STAGE(PG8_SA(0, 0), cA, voffA); PG8_STAGE(PG8_SA(0, 1), cA + hstep, voffA);
;         if (wr == 1) PG8_BAR;
;         PG8_WAIT_V(2); PG8_BAR;
;         PG8_STAGE(PG8_SB(1, 0), cB + kstep, voffB); PG8_STAGE(PG8_SA(1, 0), cA + kstep, voffA); PG8_STAGE(PG8_SB(1, 1), cB + hstep + kstep, voffB);
;         PG8_WAIT_V(6); PG8_BAR;
.LBB0_41:
	s_andn2_b64 vcc, exec, s[22:23]
	s_cbranch_vccnz .LBB0_62
	v_readlane_b32 s14, v253, 5
	v_mov_b32_e32 v9, v238
	v_readlane_b32 s15, v253, 6
	s_andn2_b64 vcc, exec, s[14:15]
	v_readfirstlane_b32 s22, v9
	s_cbranch_vccnz .LBB0_62
	v_lshlrev_b32_e32 v0, 4, v9
	v_add_u32_e32 v1, 0x2000, v0
	v_ashrrev_i32_e32 v2, 31, v1
	v_lshrrev_b32_e32 v2, 22, v2
	v_add_u32_e32 v2, v1, v2
	v_ashrrev_i32_e32 v8, 10, v2
	v_mul_i32_i24_e32 v2, 0x400, v8
	v_sub_u32_e32 v1, v1, v2
	v_lshrrev_b32_e32 v2, 4, v1
	v_bitop3_b32 v1, v2, v1, 32 bitop3:0x6c
	v_ashrrev_i32_e32 v2, 31, v1
	v_lshrrev_b32_e32 v2, 26, v2
	v_add_u32_e32 v2, v1, v2
	v_lshlrev_b32_e32 v3, 3, v8
	v_ashrrev_i32_e32 v10, 6, v2
	v_and_b32_e32 v3, -16, v3
	v_add_u32_e32 v3, v10, v3
	v_and_b32_e32 v4, 3, v10
	s_mov_b32 s12, 0xfffe0
	v_lshrrev_b32_e32 v5, 2, v3
	v_lshlrev_b32_e32 v6, 1, v3
	v_and_or_b32 v4, v3, s12, v4
	v_and_b32_e32 v5, 4, v5
	v_and_b32_e32 v6, 24, v6
	v_and_b32_e32 v2, 0xc0, v2
	v_or3_b32 v4, v4, v5, v6
	v_sub_u32_e32 v1, v1, v2
	v_mov_b32_e32 v6, 1
	v_lshlrev_b32_e32 v5, 5, v8
	v_ashrrev_i16_sdwa v1, v6, sext(v1) dst_sel:DWORD dst_unused:UNUSED_PAD src0_sel:DWORD src1_sel:BYTE_0
	v_and_b32_e32 v5, 32, v5
	v_bfe_i32 v11, v1, 0, 16
	v_add_lshl_u32 v1, v5, v11, 1
	v_lshl_add_u32 v144, v4, 12, v1
	v_lshl_add_u32 v146, v3, 12, v1
	v_bfe_i32 v1, v9, 27, 1
	v_lshrrev_b32_e32 v1, 22, v1
	v_add_u32_e32 v1, v0, v1
	v_and_b32_e32 v1, 0xfffffc00, v1
	v_sub_u32_e32 v0, v0, v1
	v_lshrrev_b32_e32 v1, 4, v0
	v_bitop3_b32 v1, v1, v0, 32 bitop3:0x6c
	v_ashrrev_i32_e32 v0, 31, v0
	v_lshrrev_b32_e32 v0, 26, v0
	v_add_u32_e32 v0, v1, v0
	v_ashrrev_i32_e32 v12, 6, v0
	v_ashrrev_i32_e32 v0, 31, v9
	v_lshrrev_b32_e32 v0, 26, v0
	v_add_u32_e32 v0, v9, v0
	v_ashrrev_i32_e32 v13, 6, v0
	v_lshlrev_b32_e32 v0, 3, v13
	v_and_b32_e32 v0, -16, v0
	v_add_u32_e32 v0, v12, v0
	s_and_b64 s[14:15], s[44:45], exec
	s_mov_b32 s2, 0x6400000
	v_and_b32_e32 v2, 3, v12
	v_lshrrev_b32_e32 v3, 2, v0
	v_lshlrev_b32_e32 v4, 1, v0
	s_cselect_b32 s2, s2, 0x4400000
	v_and_or_b32 v2, v0, s12, v2
	v_and_b32_e32 v3, 4, v3
	v_and_b32_e32 v4, 24, v4
	s_add_u32 s2, s54, s2
	v_or3_b32 v2, v2, v3, v4
	v_mul_i32_i24_e32 v4, 64, v12
	s_addc_u32 s7, s55, 0
	s_ashr_i32 s24, s22, 6
	v_sub_u32_e32 v1, v1, v4
	s_ashr_i32 s23, s22, 8
	s_lshl_b32 s8, s24, 10
	v_lshlrev_b32_e32 v3, 5, v13
	v_ashrrev_i16_sdwa v1, v6, sext(v1) dst_sel:DWORD dst_unused:UNUSED_PAD src0_sel:DWORD src1_sel:BYTE_0
	v_readlane_b32 s14, v254, 19
	v_and_b32_e32 v3, 32, v3
	v_bfe_i32 v14, v1, 0, 16
	v_readlane_b32 s15, v254, 20
	s_nop 0
	s_sub_u32 s14, 0x1f00000, s14
	s_subb_u32 s15, 0, s15
	s_add_u32 s50, s2, s14
	v_add_lshl_u32 v1, v3, v14, 1
	s_addc_u32 s51, s7, s15
	s_add_i32 s12, s8, 0
	v_lshl_add_u32 v194, v2, 12, v1
	s_add_i32 m0, s12, 0x10000
	v_lshl_add_u32 v148, v0, 12, v1
	global_load_lds_dwordx4 v194, s[50:51]
	s_add_i32 m0, s12, 0x12000
	s_add_u32 s14, s50, 0x80000
	global_load_lds_dwordx4 v144, s[50:51]
	s_addc_u32 s15, s51, 0
	s_add_i32 m0, s12, 0x14000
	v_mov_b32_e32 v145, v195
	global_load_lds_dwordx4 v194, s[14:15]
	s_add_i32 m0, s12, 0x16000
	v_mov_b32_e32 v149, v195
	global_load_lds_dwordx4 v144, s[14:15]
	v_readlane_b32 s14, v254, 41
	v_readlane_b32 s15, v254, 42
	s_add_u32 s42, s74, s14
	s_addc_u32 s43, s75, s15
	s_add_i32 s20, s12, 0x2000
	s_mov_b32 m0, s12
	s_add_u32 s14, s42, 0x80000
	global_load_lds_dwordx4 v148, s[42:43]
	s_mov_b32 m0, s20
	s_addc_u32 s15, s43, 0
	s_add_i32 s21, s12, 0x4000
	global_load_lds_dwordx4 v146, s[42:43]
	s_mov_b32 m0, s21
	s_add_i32 s48, s12, 0x6000
	global_load_lds_dwordx4 v148, s[14:15]
	s_mov_b32 m0, s48
	v_mov_b32_e32 v147, v195
	global_load_lds_dwordx4 v146, s[14:15]
	s_cmp_eq_u32 s23, 1
	v_lshl_add_u64 v[6:7], s[50:51], 0, v[194:195]
	v_lshl_add_u64 v[4:5], s[50:51], 0, v[144:145]
	v_lshl_add_u64 v[0:1], s[42:43], 0, v[148:149]
	s_cselect_b64 s[14:15], -1, 0
	s_cmp_lg_u32 s23, 1
	v_lshl_add_u64 v[2:3], s[42:43], 0, v[146:147]
	v_readlane_b32 s28, v255, 17
	v_readlane_b32 s29, v255, 18
	s_cbranch_scc1 .LBB0_45
	s_barrier
.LBB0_45:
	s_and_b64 s[26:27], s[44:45], exec
	s_cselect_b32 s25, 0x38000, 0
	s_add_u32 s49, s28, s25
	s_addc_u32 s54, s29, 0
	s_and_b32 s24, s24, 3
	s_add_i32 m0, s12, 0x18000
	v_lshl_add_u64 v[6:7], v[6:7], 0, s[30:31]
	s_lshl_b32 s26, s23, 13
	s_lshl_b32 s27, s24, 5
	s_lshl_b32 s28, s24, 12
	s_waitcnt vmcnt(2)
	s_barrier
	global_load_lds_dwordx4 v[6:7], off
	v_lshl_add_u64 v[4:5], v[4:5], 0, s[30:31]
	s_add_i32 m0, s12, 0x1a000
	s_add_i32 s55, s12, 0x8000
	s_add_i32 s60, s12, 0xa000
	global_load_lds_dwordx4 v[4:5], off
	v_lshl_add_u64 v[0:1], v[0:1], 0, s[30:31]
	s_mov_b32 m0, s55
	s_add_u32 s24, s50, 0x80080
	global_load_lds_dwordx4 v[0:1], off
	v_lshl_add_u64 v[0:1], v[2:3], 0, s[30:31]
	s_mov_b32 m0, s60
	s_addc_u32 s25, s51, 0
	global_load_lds_dwordx4 v[0:1], off
	s_add_i32 m0, s12, 0x1c000
	v_lshl_add_u64 v[0:1], s[24:25], 0, v[194:195]
	global_load_lds_dwordx4 v[0:1], off
	v_lshl_add_u64 v[0:1], s[24:25], 0, v[144:145]
	s_add_i32 m0, s12, 0x1e000
	v_bfe_u32 v2, v9, 4, 2
	global_load_lds_dwordx4 v[0:1], off
	v_and_b32_e32 v1, 15, v9
	v_lshlrev_b32_e32 v3, 4, v2
	v_lshl_or_b32 v162, s23, 6, v1
	v_lshl_or_b32 v1, v1, 6, v3
	v_lshlrev_b32_e32 v3, 2, v9
	v_and_b32_e32 v3, 32, v3
	v_bitop3_b32 v4, v1, s26, v3 bitop3:0xde
	v_bitop3_b32 v163, v1, s28, v3 bitop3:0xde
	v_readlane_b32 s24, v255, 21
	v_lshlrev_b32_e32 v1, 15, v13
	v_lshlrev_b32_e32 v0, 3, v2
	v_lshlrev_b32_e32 v2, 5, v2
	v_mov_b32_e32 v3, v195
	v_readlane_b32 s25, v255, 22
	v_and_b32_e32 v1, 0xffff0000, v1
	v_lshl_add_u32 v1, v12, 12, v1
	v_lshl_add_u64 v[150:151], s[24:25], 0, v[2:3]
	v_and_b32_e32 v2, 1, v13
	v_lshl_or_b32 v1, v2, 6, v1
	v_lshl_add_u32 v152, v14, 1, v1
	v_lshlrev_b32_e32 v1, 15, v8
	v_and_b32_e32 v1, 0xffff0000, v1
	s_waitcnt vmcnt(6)
	v_lshl_add_u32 v1, v10, 12, v1
	v_and_b32_e32 v2, 1, v8
	s_cmpk_lt_u32 s22, 0x100
	v_lshl_or_b32 v1, v2, 6, v1
	v_readlane_b32 s24, v254, 39
	s_mov_b32 s61, 0
	s_cselect_b64 s[22:23], -1, 0
	v_or_b32_e32 v164, s27, v0
	v_mov_b32_e32 v153, v195
	v_lshl_add_u32 v154, v11, 1, v1
	v_mov_b32_e32 v155, v195
	v_add_u32_e32 v165, 0, v4
	s_lshl_b32 s62, s27, 2
	v_lshlrev_b32_e32 v166, 2, v0
	v_readlane_b32 s64, v254, 18
	s_mov_b32 s63, s24
	s_sub_i32 s64, 31, s64
	s_barrier
	v_readlane_b32 s25, v254, 40
	s_branch .LBB0_48

;     __host__ __device__ bool next(int i, Unit& u) const {
;     ...
;         int wgid = (int)L; { const int q = nwg / NXCD, r = nwg % NXCD, xcd = wgid % NXCD, off = wgid / NXCD; wgid = (xcd < r ? xcd * (q + 1) : r * (q + 1) + (xcd - r) * q) + off; }
;         const int nig = WGM * nN, gid = wgid / nig, fm = gid * WGM, gsz = (nM - fm) < WGM ? (nM - fm) : WGM;
;         u.pm = fm + ((wgid % nig) % gsz); u.pn = (wgid % nig) / gsz; return true;
.LBB0_53:
	s_ashr_i32 s24, s26, 3
	s_add_i32 s24, s28, s24
	s_ashr_i32 s25, s24, 31
	s_lshr_b32 s25, s25, 24
	s_add_i32 s25, s24, s25
	s_ashr_i32 s26, s25, 8
	s_lshl_b32 s26, s26, 3
	s_sub_i32 s27, 64, s26
	s_min_i32 s27, s27, 8
	s_abs_i32 s28, s27
	v_cvt_f32_u32_e32 v0, s28
	s_sub_i32 s36, 0, s28
	s_and_b32 s25, s25, 0xffffff00
	s_sub_i32 s25, s24, s25
	v_rcp_iflag_f32_e32 v0, v0
	s_abs_i32 s24, s25
	s_xor_b32 s29, s25, s27
	s_ashr_i32 s29, s29, 31
	v_mul_f32_e32 v0, 0x4f7ffffe, v0
	v_cvt_u32_f32_e32 v0, v0
	s_nop 0
	v_readfirstlane_b32 s37, v0
	s_mul_i32 s36, s36, s37
	s_mul_hi_u32 s36, s37, s36
	s_add_i32 s37, s37, s36
	s_mul_hi_u32 s36, s24, s37
	s_mul_i32 s37, s36, s28
	s_sub_i32 s24, s24, s37
	s_add_i32 s38, s36, 1
	s_sub_i32 s37, s24, s28
	s_cmp_ge_u32 s24, s28
	s_cselect_b32 s36, s38, s36
	s_cselect_b32 s24, s37, s24
	s_add_i32 s37, s36, 1
	s_cmp_ge_u32 s24, s28
	s_cselect_b32 s24, s37, s36
	s_xor_b32 s24, s24, s29
	s_sub_i32 s24, s24, s29
	s_mul_i32 s27, s24, s27
	s_sub_i32 s25, s25, s27
	s_add_i32 s26, s26, s25
	s_sub_i32 s24, 31, s24
